# v36 plus redundant canonicalizing v_max pairs removed after the attention row-max lane swap
# baseline (speedup 1.0000x reference)
.LBB0_484:
	ds_read_b128 v[2:5], v186
	ds_read_b128 v[6:9], v186 offset:32
	ds_read_b128 v[10:13], v186 offset:64
	ds_read_b128 v[80:83], v186 offset:96
	ds_read_b128 v[216:219], v186 offset:128
	ds_read_b128 v[84:87], v186 offset:160
	ds_read_b128 v[88:91], v186 offset:192
	ds_read_b128 v[92:95], v186 offset:224
	s_waitcnt lgkmcnt(4)
	v_sub_f32_e32 v111, v83, v201
	v_sub_f32_e32 v110, v82, v201
	v_sub_f32_e32 v109, v81, v201
	v_sub_f32_e32 v108, v80, v201
	v_sub_f32_e32 v107, v13, v201
	v_sub_f32_e32 v106, v12, v201
	v_sub_f32_e32 v105, v11, v201
	v_sub_f32_e32 v104, v10, v201
	v_sub_f32_e32 v103, v9, v201
	v_sub_f32_e32 v102, v8, v201
	v_sub_f32_e32 v101, v7, v201
	v_sub_f32_e32 v100, v6, v201
	v_sub_f32_e32 v99, v5, v201
	v_sub_f32_e32 v98, v4, v201
	v_sub_f32_e32 v97, v3, v201
	v_sub_f32_e32 v96, v2, v201
	s_waitcnt lgkmcnt(0)
	v_sub_f32_e32 v95, v95, v201
	v_sub_f32_e32 v94, v94, v201
	v_sub_f32_e32 v93, v93, v201
	v_sub_f32_e32 v92, v92, v201
	v_sub_f32_e32 v91, v91, v201
	v_sub_f32_e32 v90, v90, v201
	v_sub_f32_e32 v89, v89, v201
	v_sub_f32_e32 v88, v88, v201
	v_sub_f32_e32 v87, v87, v201
	v_sub_f32_e32 v86, v86, v201
	v_sub_f32_e32 v85, v85, v201
	v_sub_f32_e32 v84, v84, v201
	v_sub_f32_e32 v83, v219, v201
	v_sub_f32_e32 v82, v218, v201
	v_sub_f32_e32 v81, v217, v201
	v_sub_f32_e32 v80, v216, v201
	v_add_u32_e32 v1, s6, v199
	ds_read_b64_tr_b16 v[2:3], v1 offset:24576
	ds_read_b64_tr_b16 v[4:5], v1 offset:25088
	v_mfma_f32_32x32x16_bf16 v[96:111], v[172:175], v[132:135], v[96:111]
	v_add_f32_e32 v6, v64, v65
	v_add_f32_e32 v6, v66, v6
	v_add_f32_e32 v6, v67, v6
	v_add_f32_e32 v6, v68, v6
	v_add_f32_e32 v10, v69, v6
	v_cvt_pk_bf16_f32 v140, v64, v65
	v_cvt_pk_bf16_f32 v141, v66, v67
	ds_read_b64_tr_b16 v[6:7], v1 offset:28672
	ds_read_b64_tr_b16 v[8:9], v1 offset:29184
	v_mfma_f32_32x32x16_bf16 v[80:95], v[168:171], v[132:135], v[80:95]
	v_add_f32_e32 v10, v70, v10
	v_add_f32_e32 v10, v71, v10
	v_add_f32_e32 v10, v72, v10
	v_add_f32_e32 v14, v73, v10
	v_cvt_pk_bf16_f32 v142, v68, v69
	v_cvt_pk_bf16_f32 v143, v70, v71
	ds_read_b64_tr_b16 v[10:11], v1 offset:25600
	ds_read_b64_tr_b16 v[12:13], v1 offset:26112
	v_mfma_f32_32x32x16_bf16 v[96:111], v[164:167], v[120:123], v[96:111]
	v_add_f32_e32 v14, v74, v14
	v_add_f32_e32 v14, v75, v14
	v_add_f32_e32 v14, v76, v14
	v_add_f32_e32 v14, v77, v14
	v_cvt_pk_bf16_f32 v136, v72, v73
	v_cvt_pk_bf16_f32 v137, v74, v75
	ds_read_b64_tr_b16 v[64:65], v1 offset:29696
	ds_read_b64_tr_b16 v[66:67], v1 offset:30208
	v_mfma_f32_32x32x16_bf16 v[80:95], v[160:163], v[120:123], v[80:95]
	v_add_f32_e32 v14, v78, v14
	v_add_f32_e32 v14, v79, v14
	v_add_f32_e32 v14, v48, v14
	v_add_f32_e32 v14, v49, v14
	v_cvt_pk_bf16_f32 v138, v76, v77
	v_cvt_pk_bf16_f32 v139, v78, v79
	ds_read_b64_tr_b16 v[68:69], v1 offset:26624
	ds_read_b64_tr_b16 v[70:71], v1 offset:27136
	v_mfma_f32_32x32x16_bf16 v[96:111], v[156:159], v[116:119], v[96:111]
	v_add_f32_e32 v14, v50, v14
	v_add_f32_e32 v14, v51, v14
	v_add_f32_e32 v14, v52, v14
	v_add_f32_e32 v14, v53, v14
	v_cvt_pk_bf16_f32 v128, v48, v49
	v_cvt_pk_bf16_f32 v129, v50, v51
	ds_read_b64_tr_b16 v[48:49], v1 offset:30720
	ds_read_b64_tr_b16 v[50:51], v1 offset:31232
	v_mfma_f32_32x32x16_bf16 v[80:95], v[152:155], v[116:119], v[80:95]
	v_add_f32_e32 v14, v54, v14
	v_add_f32_e32 v14, v55, v14
	v_add_f32_e32 v14, v56, v14
	v_add_f32_e32 v14, v57, v14
	v_cvt_pk_bf16_f32 v130, v52, v53
	v_cvt_pk_bf16_f32 v131, v54, v55
	ds_read_b64_tr_b16 v[52:53], v1 offset:27648
	ds_read_b64_tr_b16 v[54:55], v1 offset:28160
	v_mfma_f32_32x32x16_bf16 v[96:111], v[148:151], v[112:115], v[96:111]
	v_add_f32_e32 v14, v58, v14
	v_add_f32_e32 v14, v59, v14
	v_add_f32_e32 v14, v60, v14
	v_add_f32_e32 v14, v61, v14
	v_cvt_pk_bf16_f32 v124, v56, v57
	v_cvt_pk_bf16_f32 v125, v58, v59
	ds_read_b64_tr_b16 v[56:57], v1 offset:31744
	ds_read_b64_tr_b16 v[58:59], v1 offset:32256
	v_mfma_f32_32x32x16_bf16 v[80:95], v[144:147], v[112:115], v[80:95]
	v_add_f32_e32 v1, v62, v14
	v_add_f32_e32 v1, v63, v1
	v_add_f32_e32 v1, 0, v1
	v_cvt_pk_bf16_f32 v126, v60, v61
	v_cvt_pk_bf16_f32 v127, v62, v63
	v_lshl_add_u64 v[14:15], v[182:183], 0, s[58:59]
	s_add_i32 s6, s18, s39
	s_mov_b32 s7, m0
	s_mov_b32 m0, s6
	s_nop 0
	global_load_lds_dwordx4 v[14:15], off
	s_mov_b32 m0, s7
	v_lshl_add_u64 v[14:15], v[180:181], 0, s[58:59]
	s_add_i32 s6, s14, s42
	s_mov_b32 s7, m0
	s_mov_b32 m0, s6
	s_nop 0
	global_load_lds_dwordx4 v[14:15], off
	s_mov_b32 m0, s7
	v_max_f32_e32 v14, v97, v97
	v_max_f32_e32 v15, v96, v96
	v_max_f32_e32 v14, v15, v14
	v_max3_f32 v15, v98, v99, v81
	v_max3_f32 v14, v14, v80, v82
	v_max3_f32 v14, v14, v83, v100
	v_max3_f32 v15, v15, v102, v103
	v_max3_f32 v14, v14, v101, v84
	v_max3_f32 v15, v15, v86, v87
	v_max3_f32 v14, v14, v85, v104
	v_max3_f32 v15, v15, v106, v107
	v_max3_f32 v14, v14, v105, v88
	v_max3_f32 v15, v15, v90, v91
	v_max3_f32 v14, v14, v89, v108
	v_max3_f32 v15, v15, v110, v111
	v_max3_f32 v14, v14, v109, v92
	v_max3_f32 v15, v15, v94, v95
	v_max3_f32 v14, v14, v93, v15
	v_mov_b32_e32 v15, v14
	s_nop 1
	v_permlane32_swap_b32_e32 v14, v15
	v_max_f32_e32 v14, v14, v15
	v_cmp_lt_f32_e32 vcc, s96, v14
	s_cmp_lg_u64 vcc, 0
	v_add_f32_e32 v1, v203, v1
	s_cselect_b64 s[6:7], -1, 0
	s_cbranch_vccnz .LBB0_492

.LBB0_503:
	v_max_f32_e32 v60, v97, v97
	v_max_f32_e32 v61, v96, v96
	v_max_f32_e32 v60, v61, v60
	v_max3_f32 v61, v98, v99, v81
	v_max3_f32 v60, v60, v80, v82
	v_max3_f32 v60, v60, v83, v100
	v_max3_f32 v61, v61, v102, v103
	v_max3_f32 v60, v60, v101, v84
	v_max3_f32 v61, v61, v86, v87
	v_max3_f32 v60, v60, v85, v104
	v_max3_f32 v61, v61, v106, v107
	v_max3_f32 v60, v60, v105, v88
	v_max3_f32 v61, v61, v90, v91
	v_max3_f32 v60, v60, v89, v108
	v_max3_f32 v61, v61, v110, v111
	v_max3_f32 v60, v60, v109, v92
	v_max3_f32 v61, v61, v94, v95
	v_max3_f32 v60, v60, v93, v61
	v_mov_b32_e32 v61, v60
	s_nop 1
	v_permlane32_swap_b32_e32 v60, v61
	v_max_f32_e32 v60, v60, v61
	s_add_i32 s6, s63, s42
	s_mov_b32 s7, m0
	s_mov_b32 m0, s6
	s_nop 0
	global_load_lds_dwordx4 v[14:15], off
	s_mov_b32 m0, s7
	v_cmp_lt_f32_e32 vcc, s96, v60
	s_cmp_lg_u64 vcc, 0
	v_add_f32_e32 v203, v203, v72
	s_cselect_b64 s[6:7], -1, 0
	s_cbranch_vccnz .LBB0_539

.LBB0_512:
	v_add_f32_e32 v203, v203, v80
	v_max_f32_e32 v80, v65, v65
	v_max_f32_e32 v81, v64, v64
	v_max_f32_e32 v80, v81, v80
	v_max3_f32 v81, v66, v67, v49
	v_max3_f32 v80, v80, v48, v50
	v_max3_f32 v80, v80, v51, v68
	v_max3_f32 v81, v81, v70, v71
	v_max3_f32 v80, v80, v69, v52
	v_max3_f32 v81, v81, v54, v55
	v_max3_f32 v80, v80, v53, v72
	v_max3_f32 v81, v81, v74, v75
	v_max3_f32 v80, v80, v73, v56
	v_max3_f32 v81, v81, v58, v59
	v_max3_f32 v80, v80, v57, v76
	v_max3_f32 v81, v81, v78, v79
	v_max3_f32 v80, v80, v77, v60
	v_max3_f32 v81, v81, v62, v63
	v_max3_f32 v80, v80, v61, v81
	v_mov_b32_e32 v81, v80
	s_nop 1
	v_permlane32_swap_b32_e32 v80, v81
	v_max_f32_e32 v80, v80, v81
	v_cmp_lt_f32_e32 vcc, s96, v80
	s_cmp_lg_u64 vcc, 0
	s_cselect_b64 s[16:17], -1, 0
	s_cbranch_vccnz .LBB0_542

.LBB0_546:
	v_lshl_add_u32 v1, s60, 2, v200
	v_add_u32_e32 v2, 0xffffff00, v1
	v_add_u32_e32 v6, 0xffffff80, v1
	v_add_u32_e32 v10, 0xffffff20, v1
	v_add_u32_e32 v14, 0xffffffa0, v1
	ds_read_b128 v[2:5], v2
	ds_read_b128 v[6:9], v6
	ds_read_b128 v[10:13], v10
	ds_read_b128 v[96:99], v14
	v_add_u32_e32 v14, 0xffffff40, v1
	v_subrev_u32_e32 v15, 64, v1
	v_add_u32_e32 v80, 0xffffff60, v1
	v_subrev_u32_e32 v1, 32, v1
	ds_read_b128 v[80:83], v80
	ds_read_b128 v[84:87], v14
	ds_read_b128 v[100:103], v15
	ds_read_b128 v[104:107], v1
	s_waitcnt lgkmcnt(3)
	v_sub_f32_e32 v95, v83, v201
	v_sub_f32_e32 v94, v82, v201
	v_sub_f32_e32 v93, v81, v201
	v_sub_f32_e32 v92, v80, v201
	s_waitcnt lgkmcnt(2)
	v_sub_f32_e32 v91, v87, v201
	v_sub_f32_e32 v90, v86, v201
	v_sub_f32_e32 v89, v85, v201
	v_sub_f32_e32 v88, v84, v201
	v_sub_f32_e32 v87, v13, v201
	v_sub_f32_e32 v86, v12, v201
	v_sub_f32_e32 v85, v11, v201
	v_sub_f32_e32 v84, v10, v201
	v_sub_f32_e32 v83, v5, v201
	v_sub_f32_e32 v82, v4, v201
	v_sub_f32_e32 v81, v3, v201
	v_sub_f32_e32 v80, v2, v201
	s_waitcnt lgkmcnt(0)
	v_sub_f32_e32 v111, v107, v201
	v_sub_f32_e32 v110, v106, v201
	v_sub_f32_e32 v109, v105, v201
	v_sub_f32_e32 v108, v104, v201
	v_sub_f32_e32 v107, v103, v201
	v_sub_f32_e32 v106, v102, v201
	v_sub_f32_e32 v105, v101, v201
	v_sub_f32_e32 v104, v100, v201
	v_sub_f32_e32 v103, v99, v201
	v_sub_f32_e32 v102, v98, v201
	v_sub_f32_e32 v101, v97, v201
	v_sub_f32_e32 v100, v96, v201
	v_sub_f32_e32 v99, v9, v201
	v_sub_f32_e32 v98, v8, v201
	v_sub_f32_e32 v97, v7, v201
	v_sub_f32_e32 v96, v6, v201
	v_add_u32_e32 v1, s63, v199
	ds_read_b64_tr_b16 v[2:3], v1 offset:24576
	ds_read_b64_tr_b16 v[4:5], v1 offset:25088
	v_mfma_f32_32x32x16_bf16 v[80:95], v[172:175], v[132:135], v[80:95]
	v_add_f32_e32 v6, v64, v65
	v_add_f32_e32 v6, v66, v6
	v_add_f32_e32 v6, v67, v6
	v_add_f32_e32 v6, v68, v6
	v_add_f32_e32 v10, v69, v6
	v_cvt_pk_bf16_f32 v140, v64, v65
	v_cvt_pk_bf16_f32 v141, v66, v67
	ds_read_b64_tr_b16 v[6:7], v1 offset:28672
	ds_read_b64_tr_b16 v[8:9], v1 offset:29184
	v_mfma_f32_32x32x16_bf16 v[96:111], v[168:171], v[132:135], v[96:111]
	v_add_f32_e32 v10, v70, v10
	v_add_f32_e32 v10, v71, v10
	v_add_f32_e32 v10, v72, v10
	v_add_f32_e32 v14, v73, v10
	v_cvt_pk_bf16_f32 v142, v68, v69
	v_cvt_pk_bf16_f32 v143, v70, v71
	ds_read_b64_tr_b16 v[10:11], v1 offset:25600
	ds_read_b64_tr_b16 v[12:13], v1 offset:26112
	v_mfma_f32_32x32x16_bf16 v[80:95], v[164:167], v[120:123], v[80:95]
	v_add_f32_e32 v14, v74, v14
	v_add_f32_e32 v14, v75, v14
	v_add_f32_e32 v14, v76, v14
	v_add_f32_e32 v14, v77, v14
	v_cvt_pk_bf16_f32 v136, v72, v73
	v_cvt_pk_bf16_f32 v137, v74, v75
	ds_read_b64_tr_b16 v[64:65], v1 offset:29696
	ds_read_b64_tr_b16 v[66:67], v1 offset:30208
	v_mfma_f32_32x32x16_bf16 v[96:111], v[160:163], v[120:123], v[96:111]
	v_add_f32_e32 v14, v78, v14
	v_add_f32_e32 v14, v79, v14
	v_add_f32_e32 v14, v48, v14
	v_add_f32_e32 v14, v49, v14
	v_cvt_pk_bf16_f32 v138, v76, v77
	v_cvt_pk_bf16_f32 v139, v78, v79
	ds_read_b64_tr_b16 v[68:69], v1 offset:26624
	ds_read_b64_tr_b16 v[70:71], v1 offset:27136
	v_mfma_f32_32x32x16_bf16 v[80:95], v[156:159], v[116:119], v[80:95]
	v_add_f32_e32 v14, v50, v14
	v_add_f32_e32 v14, v51, v14
	v_add_f32_e32 v14, v52, v14
	v_add_f32_e32 v14, v53, v14
	v_cvt_pk_bf16_f32 v128, v48, v49
	v_cvt_pk_bf16_f32 v129, v50, v51
	ds_read_b64_tr_b16 v[48:49], v1 offset:30720
	ds_read_b64_tr_b16 v[50:51], v1 offset:31232
	v_mfma_f32_32x32x16_bf16 v[96:111], v[152:155], v[116:119], v[96:111]
	v_add_f32_e32 v14, v54, v14
	v_add_f32_e32 v14, v55, v14
	v_add_f32_e32 v14, v56, v14
	v_add_f32_e32 v14, v57, v14
	v_cvt_pk_bf16_f32 v130, v52, v53
	v_cvt_pk_bf16_f32 v131, v54, v55
	ds_read_b64_tr_b16 v[52:53], v1 offset:27648
	ds_read_b64_tr_b16 v[54:55], v1 offset:28160
	v_mfma_f32_32x32x16_bf16 v[80:95], v[148:151], v[112:115], v[80:95]
	v_add_f32_e32 v14, v58, v14
	v_add_f32_e32 v14, v59, v14
	v_add_f32_e32 v14, v60, v14
	v_add_f32_e32 v14, v61, v14
	v_cvt_pk_bf16_f32 v124, v56, v57
	v_cvt_pk_bf16_f32 v125, v58, v59
	ds_read_b64_tr_b16 v[56:57], v1 offset:31744
	ds_read_b64_tr_b16 v[58:59], v1 offset:32256
	v_mfma_f32_32x32x16_bf16 v[96:111], v[144:147], v[112:115], v[96:111]
	v_add_f32_e32 v1, v62, v14
	v_add_f32_e32 v1, v63, v1
	v_add_f32_e32 v1, 0, v1
	v_cvt_pk_bf16_f32 v126, v60, v61
	v_cvt_pk_bf16_f32 v127, v62, v63
	v_max_f32_e32 v14, v81, v81
	v_max_f32_e32 v15, v80, v80
	v_max_f32_e32 v14, v15, v14
	s_nop 3
	v_max3_f32 v15, v82, v83, v97
	v_max3_f32 v14, v14, v96, v98
	v_max3_f32 v14, v14, v99, v84
	v_max3_f32 v15, v15, v86, v87
	v_max3_f32 v14, v14, v85, v100
	v_max3_f32 v15, v15, v102, v103
	v_max3_f32 v14, v14, v101, v88
	v_max3_f32 v15, v15, v90, v91
	v_max3_f32 v14, v14, v89, v104
	v_max3_f32 v15, v15, v106, v107
	v_max3_f32 v14, v14, v105, v92
	v_max3_f32 v15, v15, v94, v95
	v_max3_f32 v14, v14, v93, v108
	v_max3_f32 v15, v15, v110, v111
	v_max3_f32 v14, v14, v109, v15
	v_mov_b32_e32 v15, v14
	s_nop 1
	v_permlane32_swap_b32_e32 v14, v15
	v_max_f32_e32 v14, v14, v15
	v_cmp_lt_f32_e32 vcc, s96, v14
	s_cmp_lg_u64 vcc, 0
	v_add_f32_e32 v1, v203, v1
	s_cselect_b64 s[4:5], -1, 0
	s_cbranch_vccnz .LBB0_559
